# diff-attn loop: max tree via v_max3 without canonicalize, s1 exps interleaved under first 8 PV MFMAs, pk_add row sums
# speedup vs baseline: 1.0182x; 1.0182x over previous
; __device__ __forceinline__ void diff_unit(const Frame& F, int b, int h, int qi, float lam, int dry) {
;     ...
;             float mx = fmaxf(s0[0], s1[0]);
; #pragma unroll
;             for (int r = 1; r < 16; ++r) mx = fmaxf(mx, fmaxf(s0[r], s1[r]));
;             mx = fmaxf(mx, __shfl_xor(mx, 32));
;             const float mxs = mx * LOG2E;
;             if (__any(mxs > ms + 8.0f)) {
;                 const float msn = fmaxf(ms, mxs); const float f = __builtin_amdgcn_exp2f(ms - msn); lsum *= f; ms = msn;
; #pragma unroll
;                 for (int dt = 0; dt < 4; ++dt)
; #pragma unroll
;                     for (int r = 0; r < 16; ++r) O[dt][r] *= f;
;             }
.LBB0_303:
	v_max3_f32 v223, v80, v81, v82
	v_max3_f32 v223, v223, v83, v84
	v_max3_f32 v223, v223, v85, v86
	v_max3_f32 v223, v223, v87, v88
	v_max3_f32 v223, v223, v89, v90
	v_max3_f32 v223, v223, v91, v92
	v_max3_f32 v223, v223, v93, v94
	s_nop 2
	v_max3_f32 v224, v64, v65, v66
	v_max3_f32 v224, v224, v67, v68
	v_max3_f32 v224, v224, v69, v70
	v_max3_f32 v224, v224, v71, v72
	v_max3_f32 v224, v224, v73, v74
	v_max3_f32 v224, v224, v75, v76
	v_max3_f32 v224, v224, v77, v78
	v_max3_f32 v223, v223, v224, v95
	v_max_f32_e32 v223, v223, v79
	ds_bpermute_b32 v224, v155, v223
	s_waitcnt lgkmcnt(0)
	v_max_f32_e32 v223, v223, v224
	v_mul_f32_e32 v223, 0x3fb8aa3b, v223
	v_add_f32_e32 v224, 0x41000000, v185
	v_cmp_gt_f32_e32 vcc, v223, v224
	s_cbranch_vccz .LBB0_305
	v_max_f32_e32 v223, v223, v223
	v_max_f32_e32 v224, v185, v185
	v_max_f32_e32 v223, v224, v223
	v_sub_f32_e32 v185, v185, v223
	v_exp_f32_e32 v224, v185
	v_mov_b32_e32 v185, v223
	v_pk_mul_f32 v[62:63], v[62:63], v[224:225] op_sel_hi:[1,0]
	v_pk_mul_f32 v[60:61], v[60:61], v[224:225] op_sel_hi:[1,0]
	v_pk_mul_f32 v[58:59], v[58:59], v[224:225] op_sel_hi:[1,0]
	v_pk_mul_f32 v[56:57], v[56:57], v[224:225] op_sel_hi:[1,0]
	v_pk_mul_f32 v[54:55], v[54:55], v[224:225] op_sel_hi:[1,0]
	v_pk_mul_f32 v[52:53], v[52:53], v[224:225] op_sel_hi:[1,0]
	v_pk_mul_f32 v[50:51], v[50:51], v[224:225] op_sel_hi:[1,0]
	v_pk_mul_f32 v[48:49], v[48:49], v[224:225] op_sel_hi:[1,0]
	v_pk_mul_f32 v[46:47], v[46:47], v[224:225] op_sel_hi:[1,0]
	v_pk_mul_f32 v[44:45], v[44:45], v[224:225] op_sel_hi:[1,0]
	v_pk_mul_f32 v[42:43], v[42:43], v[224:225] op_sel_hi:[1,0]
	v_pk_mul_f32 v[40:41], v[40:41], v[224:225] op_sel_hi:[1,0]
	v_pk_mul_f32 v[38:39], v[38:39], v[224:225] op_sel_hi:[1,0]
	v_pk_mul_f32 v[36:37], v[36:37], v[224:225] op_sel_hi:[1,0]
	v_pk_mul_f32 v[34:35], v[34:35], v[224:225] op_sel_hi:[1,0]
	v_pk_mul_f32 v[32:33], v[32:33], v[224:225] op_sel_hi:[1,0]
	v_pk_mul_f32 v[30:31], v[30:31], v[224:225] op_sel_hi:[1,0]
	v_pk_mul_f32 v[28:29], v[28:29], v[224:225] op_sel_hi:[1,0]
	v_pk_mul_f32 v[26:27], v[26:27], v[224:225] op_sel_hi:[1,0]
	v_pk_mul_f32 v[24:25], v[24:25], v[224:225] op_sel_hi:[1,0]
	v_pk_mul_f32 v[22:23], v[22:23], v[224:225] op_sel_hi:[1,0]
	v_pk_mul_f32 v[20:21], v[20:21], v[224:225] op_sel_hi:[1,0]
	v_pk_mul_f32 v[18:19], v[18:19], v[224:225] op_sel_hi:[1,0]
	v_pk_mul_f32 v[16:17], v[16:17], v[224:225] op_sel_hi:[1,0]
	v_pk_mul_f32 v[14:15], v[14:15], v[224:225] op_sel_hi:[1,0]
	v_pk_mul_f32 v[12:13], v[12:13], v[224:225] op_sel_hi:[1,0]
	v_pk_mul_f32 v[10:11], v[10:11], v[224:225] op_sel_hi:[1,0]
	v_pk_mul_f32 v[8:9], v[8:9], v[224:225] op_sel_hi:[1,0]
	v_pk_mul_f32 v[6:7], v[6:7], v[224:225] op_sel_hi:[1,0]
	v_pk_mul_f32 v[4:5], v[4:5], v[224:225] op_sel_hi:[1,0]
	v_pk_mul_f32 v[2:3], v[2:3], v[224:225] op_sel_hi:[1,0]
	v_pk_mul_f32 v[0:1], v[0:1], v[224:225] op_sel_hi:[1,0]
	v_mul_f32_e32 v158, v158, v224
; #define MFMA32(a, b, c) __builtin_amdgcn_mfma_f32_32x32x16_bf16((a), (b), (c), 0, 0, 0)
; #define VFRAG(ptr, off0, STR) ({ const s16x4 lo_ = vtr((ptr) + (off0)); const s16x4 hi_ = vtr((ptr) + (off0) + 8 * (STR)); (bf16x8){lo_[0], lo_[1], lo_[2], lo_[3], hi_[0], hi_[1], hi_[2], hi_[3]}; })
; __device__ __forceinline__ void diff_unit(const Frame& F, int b, int h, int qi, float lam, int dry) {
;     ...
;             float ps = 0.f;
; #pragma unroll
;             for (int r = 0; r < 16; ++r) { s0[r] = __builtin_amdgcn_exp2f(s0[r] * LOG2E - ms); ps += s0[r]; }
;             if (!meta) {
; #pragma unroll
;                 for (int r = 0; r < 16; ++r) { s1[r] = __builtin_amdgcn_exp2f(s1[r] * LOG2E - ms); ps += s1[r]; }
;             }
;             lsum += ps;
;             __builtin_amdgcn_s_setprio(1);
;             { const bf16x8 pf = pack_step(s0, 0);
;               O[0] = MFMA32(vpre0, pf, O[0]); O[1] = MFMA32(vpre1, pf, O[1]); O[2] = MFMA32(vpre2, pf, O[2]); O[3] = MFMA32(vpre3, pf, O[3]); }
;             if (!meta) {
;                 { const bf16x8 pf = pack_step(s0, 1);
;                   O[0] = MFMA32(vprf0, pf, O[0]); O[1] = MFMA32(vprf1, pf, O[1]);
; #pragma unroll
;                   for (int dt = 2; dt < 4; ++dt) { const bf16x8 vf = VFRAG(vb, 16 * DV_STR + 64 * dt, DV_STR); O[dt] = MFMA32(vf, pf, O[dt]); } }
; #pragma unroll
;                 for (int s2 = 0; s2 < 2; ++s2) { const bf16x8 pf = pack_step(s1, s2);
; #pragma unroll
;                     for (int dt = 0; dt < 4; ++dt) { const bf16x8 vf = VFRAG(vb, (32 + 16 * s2) * DV_STR + 64 * dt, DV_STR); O[dt] = MFMA32(vf, pf, O[dt]); } }
;             }
;             __builtin_amdgcn_s_setprio(0);
.LBB0_305:
	ds_read_b64_tr_b16 v[224:225], v222 offset:40064
	ds_read_b64_tr_b16 v[226:227], v222 offset:42624
	ds_read_b64_tr_b16 v[228:229], v222 offset:40128
	ds_read_b64_tr_b16 v[230:231], v222 offset:42688
	v_fma_f32 v80, v80, s88, -v185
	v_fma_f32 v81, v81, s88, -v185
	v_fma_f32 v82, v82, s88, -v185
	v_fma_f32 v83, v83, s88, -v185
	v_exp_f32_e32 v80, v80
	v_exp_f32_e32 v81, v81
	v_exp_f32_e32 v82, v82
	v_exp_f32_e32 v83, v83
	v_fma_f32 v84, v84, s88, -v185
	v_fma_f32 v85, v85, s88, -v185
	v_fma_f32 v86, v86, s88, -v185
	v_fma_f32 v87, v87, s88, -v185
	v_exp_f32_e32 v84, v84
	v_exp_f32_e32 v85, v85
	v_exp_f32_e32 v86, v86
	v_exp_f32_e32 v87, v87
	v_pk_add_f32 v[236:237], v[80:81], v[82:83]
	v_fma_f32 v88, v88, s88, -v185
	v_fma_f32 v89, v89, s88, -v185
	v_fma_f32 v90, v90, s88, -v185
	v_fma_f32 v91, v91, s88, -v185
	v_exp_f32_e32 v88, v88
	v_exp_f32_e32 v89, v89
	v_exp_f32_e32 v90, v90
	v_exp_f32_e32 v91, v91
	v_pk_add_f32 v[236:237], v[236:237], v[84:85]
	v_pk_add_f32 v[236:237], v[236:237], v[86:87]
	v_fma_f32 v92, v92, s88, -v185
	v_fma_f32 v93, v93, s88, -v185
	v_fma_f32 v94, v94, s88, -v185
	v_fma_f32 v95, v95, s88, -v185
	v_exp_f32_e32 v92, v92
	v_exp_f32_e32 v93, v93
	v_exp_f32_e32 v94, v94
	v_exp_f32_e32 v95, v95
	v_pk_add_f32 v[236:237], v[236:237], v[88:89]
	v_pk_add_f32 v[236:237], v[236:237], v[90:91]
	s_setprio 1
	v_cvt_pk_bf16_f32 v232, v80, v81
	v_cvt_pk_bf16_f32 v233, v82, v83
	v_cvt_pk_bf16_f32 v234, v84, v85
	v_cvt_pk_bf16_f32 v235, v86, v87
	v_pk_add_f32 v[236:237], v[236:237], v[92:93]
	v_cvt_pk_bf16_f32 v80, v88, v89
	v_cvt_pk_bf16_f32 v81, v90, v91
	v_cvt_pk_bf16_f32 v82, v92, v93
	v_cvt_pk_bf16_f32 v83, v94, v95
	v_pk_add_f32 v[236:237], v[236:237], v[94:95]
	v_mfma_f32_32x32x16_bf16 v[48:63], v[148:151], v[232:235], v[48:63]
	ds_read_b64_tr_b16 v[148:149], v222 offset:45056
	ds_read_b64_tr_b16 v[150:151], v222 offset:47616
	v_fma_f32 v64, v64, s88, -v185
	v_fma_f32 v65, v65, s88, -v185
	v_exp_f32_e32 v64, v64
	v_exp_f32_e32 v65, v65
	v_mfma_f32_32x32x16_bf16 v[32:47], v[144:147], v[232:235], v[32:47]
	ds_read_b64_tr_b16 v[144:145], v222 offset:45120
	ds_read_b64_tr_b16 v[146:147], v222 offset:47680
	v_fma_f32 v66, v66, s88, -v185
	v_fma_f32 v67, v67, s88, -v185
	v_exp_f32_e32 v66, v66
	v_exp_f32_e32 v67, v67
	v_pk_add_f32 v[236:237], v[236:237], v[64:65]
	v_mfma_f32_32x32x16_bf16 v[16:31], v[140:143], v[232:235], v[16:31]
	ds_read_b64_tr_b16 v[140:141], v222 offset:45184
	ds_read_b64_tr_b16 v[142:143], v222 offset:47744
	v_fma_f32 v68, v68, s88, -v185
	v_fma_f32 v69, v69, s88, -v185
	v_exp_f32_e32 v68, v68
	v_exp_f32_e32 v69, v69
	v_pk_add_f32 v[236:237], v[236:237], v[66:67]
	v_mfma_f32_32x32x16_bf16 v[0:15], v[136:139], v[232:235], v[0:15]
	ds_read_b64_tr_b16 v[136:137], v222 offset:45248
	ds_read_b64_tr_b16 v[138:139], v222 offset:47808
	v_fma_f32 v70, v70, s88, -v185
	v_fma_f32 v71, v71, s88, -v185
	v_exp_f32_e32 v70, v70
	v_exp_f32_e32 v71, v71
	v_pk_add_f32 v[236:237], v[236:237], v[68:69]
	v_mfma_f32_32x32x16_bf16 v[48:63], v[128:131], v[80:83], v[48:63]
	ds_read_b64_tr_b16 v[128:129], v222 offset:50176
	ds_read_b64_tr_b16 v[130:131], v222 offset:52736
	v_fma_f32 v72, v72, s88, -v185
	v_fma_f32 v73, v73, s88, -v185
	v_exp_f32_e32 v72, v72
	v_exp_f32_e32 v73, v73
	v_pk_add_f32 v[236:237], v[236:237], v[70:71]
	v_mfma_f32_32x32x16_bf16 v[32:47], v[132:135], v[80:83], v[32:47]
	ds_read_b64_tr_b16 v[132:133], v222 offset:50240
	ds_read_b64_tr_b16 v[134:135], v222 offset:52800
	v_fma_f32 v74, v74, s88, -v185
	v_fma_f32 v75, v75, s88, -v185
	v_exp_f32_e32 v74, v74
	v_exp_f32_e32 v75, v75
	v_pk_add_f32 v[236:237], v[236:237], v[72:73]
	s_waitcnt lgkmcnt(14)
	v_mfma_f32_32x32x16_bf16 v[16:31], v[224:227], v[80:83], v[16:31]
	ds_read_b64_tr_b16 v[224:225], v222 offset:50304
	ds_read_b64_tr_b16 v[226:227], v222 offset:52864
	v_fma_f32 v76, v76, s88, -v185
	v_fma_f32 v77, v77, s88, -v185
	v_exp_f32_e32 v76, v76
	v_exp_f32_e32 v77, v77
	v_pk_add_f32 v[236:237], v[236:237], v[74:75]
	s_waitcnt lgkmcnt(14)
	v_mfma_f32_32x32x16_bf16 v[0:15], v[228:231], v[80:83], v[0:15]
	ds_read_b64_tr_b16 v[228:229], v222 offset:50368
	ds_read_b64_tr_b16 v[230:231], v222 offset:52928
	v_fma_f32 v78, v78, s88, -v185
	v_fma_f32 v79, v79, s88, -v185
	v_exp_f32_e32 v78, v78
	v_exp_f32_e32 v79, v79
	v_pk_add_f32 v[236:237], v[236:237], v[76:77]
	v_cvt_pk_bf16_f32 v84, v64, v65
	v_cvt_pk_bf16_f32 v85, v66, v67
	v_cvt_pk_bf16_f32 v86, v68, v69
	v_cvt_pk_bf16_f32 v87, v70, v71
	v_pk_add_f32 v[236:237], v[236:237], v[78:79]
	v_cvt_pk_bf16_f32 v232, v72, v73
	v_cvt_pk_bf16_f32 v233, v74, v75
	v_cvt_pk_bf16_f32 v234, v76, v77
	v_cvt_pk_bf16_f32 v235, v78, v79
	v_add_f32_e32 v223, v236, v237
	v_add_f32_e32 v158, v158, v223
	s_waitcnt lgkmcnt(14)
	v_mfma_f32_32x32x16_bf16 v[48:63], v[148:151], v[84:87], v[48:63]
	s_waitcnt lgkmcnt(12)
	v_mfma_f32_32x32x16_bf16 v[32:47], v[144:147], v[84:87], v[32:47]
	s_waitcnt lgkmcnt(10)
	v_mfma_f32_32x32x16_bf16 v[16:31], v[140:143], v[84:87], v[16:31]
	s_waitcnt lgkmcnt(8)
	v_mfma_f32_32x32x16_bf16 v[0:15], v[136:139], v[84:87], v[0:15]
	s_waitcnt lgkmcnt(6)
	v_mfma_f32_32x32x16_bf16 v[48:63], v[128:131], v[232:235], v[48:63]
	s_waitcnt lgkmcnt(4)
	v_mfma_f32_32x32x16_bf16 v[32:47], v[132:135], v[232:235], v[32:47]
	s_waitcnt lgkmcnt(2)
	v_mfma_f32_32x32x16_bf16 v[16:31], v[224:227], v[232:235], v[16:31]
	s_waitcnt lgkmcnt(0)
	v_mfma_f32_32x32x16_bf16 v[0:15], v[228:231], v[232:235], v[0:15]
	s_setprio 0
	s_andn2_b64 vcc, exec, s[66:67]
	s_cbranch_vccnz .LBB0_296

; __device__ __forceinline__ void diff_unit(const Frame& F, int b, int h, int qi, float lam, int dry) {
;     ...
;             float mx = fmaxf(s0[0], s1[0]);
; #pragma unroll
;             for (int r = 1; r < 16; ++r) mx = fmaxf(mx, fmaxf(s0[r], s1[r]));
;             mx = fmaxf(mx, __shfl_xor(mx, 32));
;             const float mxs = mx * LOG2E;
;             if (__any(mxs > ms + 8.0f)) {
;                 const float msn = fmaxf(ms, mxs); const float f = __builtin_amdgcn_exp2f(ms - msn); lsum *= f; ms = msn;
; #pragma unroll
;                 for (int dt = 0; dt < 4; ++dt)
; #pragma unroll
;                     for (int r = 0; r < 16; ++r) O[dt][r] *= f;
;             }
.LBB0_322:
	v_max3_f32 v189, v80, v81, v82
	v_max3_f32 v189, v189, v83, v84
	v_max3_f32 v189, v189, v85, v86
	v_max3_f32 v189, v189, v87, v88
	v_max3_f32 v189, v189, v89, v90
	v_max3_f32 v189, v189, v91, v92
	v_max3_f32 v189, v189, v93, v94
	s_nop 2
	v_max3_f32 v190, v64, v65, v66
	v_max3_f32 v190, v190, v67, v68
	v_max3_f32 v190, v190, v69, v70
	v_max3_f32 v190, v190, v71, v72
	v_max3_f32 v190, v190, v73, v74
	v_max3_f32 v190, v190, v75, v76
	v_max3_f32 v190, v190, v77, v78
	v_max3_f32 v189, v189, v190, v95
	v_max_f32_e32 v189, v189, v79
	ds_bpermute_b32 v190, v155, v189
	s_waitcnt lgkmcnt(0)
	v_max_f32_e32 v189, v189, v190
	v_mul_f32_e32 v189, 0x3fb8aa3b, v189
	v_add_f32_e32 v190, 0x41000000, v158
	v_cmp_gt_f32_e32 vcc, v189, v190
	s_cbranch_vccz .LBB0_324
	v_max_f32_e32 v189, v189, v189
	v_max_f32_e32 v190, v158, v158
	v_max_f32_e32 v189, v190, v189
	v_sub_f32_e32 v158, v158, v189
	v_exp_f32_e32 v158, v158
	s_nop 0
	v_pk_mul_f32 v[62:63], v[62:63], v[158:159] op_sel_hi:[1,0]
	v_pk_mul_f32 v[60:61], v[60:61], v[158:159] op_sel_hi:[1,0]
	v_pk_mul_f32 v[58:59], v[58:59], v[158:159] op_sel_hi:[1,0]
	v_pk_mul_f32 v[56:57], v[56:57], v[158:159] op_sel_hi:[1,0]
	v_pk_mul_f32 v[54:55], v[54:55], v[158:159] op_sel_hi:[1,0]
	v_pk_mul_f32 v[52:53], v[52:53], v[158:159] op_sel_hi:[1,0]
	v_pk_mul_f32 v[50:51], v[50:51], v[158:159] op_sel_hi:[1,0]
	v_pk_mul_f32 v[48:49], v[48:49], v[158:159] op_sel_hi:[1,0]
	v_pk_mul_f32 v[46:47], v[46:47], v[158:159] op_sel_hi:[1,0]
	v_pk_mul_f32 v[44:45], v[44:45], v[158:159] op_sel_hi:[1,0]
	v_pk_mul_f32 v[42:43], v[42:43], v[158:159] op_sel_hi:[1,0]
	v_pk_mul_f32 v[40:41], v[40:41], v[158:159] op_sel_hi:[1,0]
	v_pk_mul_f32 v[38:39], v[38:39], v[158:159] op_sel_hi:[1,0]
	v_pk_mul_f32 v[36:37], v[36:37], v[158:159] op_sel_hi:[1,0]
	v_pk_mul_f32 v[34:35], v[34:35], v[158:159] op_sel_hi:[1,0]
	v_pk_mul_f32 v[32:33], v[32:33], v[158:159] op_sel_hi:[1,0]
	v_pk_mul_f32 v[30:31], v[30:31], v[158:159] op_sel_hi:[1,0]
	v_pk_mul_f32 v[28:29], v[28:29], v[158:159] op_sel_hi:[1,0]
	v_pk_mul_f32 v[26:27], v[26:27], v[158:159] op_sel_hi:[1,0]
	v_pk_mul_f32 v[24:25], v[24:25], v[158:159] op_sel_hi:[1,0]
	v_pk_mul_f32 v[22:23], v[22:23], v[158:159] op_sel_hi:[1,0]
	v_pk_mul_f32 v[20:21], v[20:21], v[158:159] op_sel_hi:[1,0]
	v_pk_mul_f32 v[18:19], v[18:19], v[158:159] op_sel_hi:[1,0]
	v_pk_mul_f32 v[16:17], v[16:17], v[158:159] op_sel_hi:[1,0]
	v_pk_mul_f32 v[14:15], v[14:15], v[158:159] op_sel_hi:[1,0]
	v_pk_mul_f32 v[12:13], v[12:13], v[158:159] op_sel_hi:[1,0]
	v_pk_mul_f32 v[10:11], v[10:11], v[158:159] op_sel_hi:[1,0]
	v_pk_mul_f32 v[8:9], v[8:9], v[158:159] op_sel_hi:[1,0]
	v_pk_mul_f32 v[6:7], v[6:7], v[158:159] op_sel_hi:[1,0]
	v_pk_mul_f32 v[4:5], v[4:5], v[158:159] op_sel_hi:[1,0]
	v_pk_mul_f32 v[2:3], v[2:3], v[158:159] op_sel_hi:[1,0]
	v_pk_mul_f32 v[0:1], v[0:1], v[158:159] op_sel_hi:[1,0]
	v_mul_f32_e32 v153, v153, v158
	v_mov_b32_e32 v158, v189
; #define MFMA32(a, b, c) __builtin_amdgcn_mfma_f32_32x32x16_bf16((a), (b), (c), 0, 0, 0)
; #define VFRAG(ptr, off0, STR) ({ const s16x4 lo_ = vtr((ptr) + (off0)); const s16x4 hi_ = vtr((ptr) + (off0) + 8 * (STR)); (bf16x8){lo_[0], lo_[1], lo_[2], lo_[3], hi_[0], hi_[1], hi_[2], hi_[3]}; })
; __device__ __forceinline__ void diff_unit(const Frame& F, int b, int h, int qi, float lam, int dry) {
;     ...
;             float ps = 0.f;
; #pragma unroll
;             for (int r = 0; r < 16; ++r) { s0[r] = __builtin_amdgcn_exp2f(s0[r] * LOG2E - ms); ps += s0[r]; }
;             if (!meta) {
; #pragma unroll
;                 for (int r = 0; r < 16; ++r) { s1[r] = __builtin_amdgcn_exp2f(s1[r] * LOG2E - ms); ps += s1[r]; }
;             }
;             lsum += ps;
;             __builtin_amdgcn_s_setprio(1);
;             { const bf16x8 pf = pack_step(s0, 0);
;               O[0] = MFMA32(vpre0, pf, O[0]); O[1] = MFMA32(vpre1, pf, O[1]); O[2] = MFMA32(vpre2, pf, O[2]); O[3] = MFMA32(vpre3, pf, O[3]); }
;             if (!meta) {
;                 { const bf16x8 pf = pack_step(s0, 1);
;                   O[0] = MFMA32(vprf0, pf, O[0]); O[1] = MFMA32(vprf1, pf, O[1]);
; #pragma unroll
;                   for (int dt = 2; dt < 4; ++dt) { const bf16x8 vf = VFRAG(vb, 16 * DV_STR + 64 * dt, DV_STR); O[dt] = MFMA32(vf, pf, O[dt]); } }
; #pragma unroll
;                 for (int s2 = 0; s2 < 2; ++s2) { const bf16x8 pf = pack_step(s1, s2);
; #pragma unroll
;                     for (int dt = 0; dt < 4; ++dt) { const bf16x8 vf = VFRAG(vb, (32 + 16 * s2) * DV_STR + 64 * dt, DV_STR); O[dt] = MFMA32(vf, pf, O[dt]); } }
;             }
;             __builtin_amdgcn_s_setprio(0);
.LBB0_324:
	ds_read_b64_tr_b16 v[190:191], v188 offset:40064
	ds_read_b64_tr_b16 v[192:193], v188 offset:42624
	ds_read_b64_tr_b16 v[194:195], v188 offset:40128
	ds_read_b64_tr_b16 v[196:197], v188 offset:42688
	v_fma_f32 v80, v80, s88, -v158
	v_fma_f32 v81, v81, s88, -v158
	v_fma_f32 v82, v82, s88, -v158
	v_fma_f32 v83, v83, s88, -v158
	v_exp_f32_e32 v80, v80
	v_exp_f32_e32 v81, v81
	v_exp_f32_e32 v82, v82
	v_exp_f32_e32 v83, v83
	v_fma_f32 v84, v84, s88, -v158
	v_fma_f32 v85, v85, s88, -v158
	v_fma_f32 v86, v86, s88, -v158
	v_fma_f32 v87, v87, s88, -v158
	v_exp_f32_e32 v84, v84
	v_exp_f32_e32 v85, v85
	v_exp_f32_e32 v86, v86
	v_exp_f32_e32 v87, v87
	v_pk_add_f32 v[202:203], v[80:81], v[82:83]
	v_fma_f32 v88, v88, s88, -v158
	v_fma_f32 v89, v89, s88, -v158
	v_fma_f32 v90, v90, s88, -v158
	v_fma_f32 v91, v91, s88, -v158
	v_exp_f32_e32 v88, v88
	v_exp_f32_e32 v89, v89
	v_exp_f32_e32 v90, v90
	v_exp_f32_e32 v91, v91
	v_pk_add_f32 v[202:203], v[202:203], v[84:85]
	v_pk_add_f32 v[202:203], v[202:203], v[86:87]
	v_fma_f32 v92, v92, s88, -v158
	v_fma_f32 v93, v93, s88, -v158
	v_fma_f32 v94, v94, s88, -v158
	v_fma_f32 v95, v95, s88, -v158
	v_exp_f32_e32 v92, v92
	v_exp_f32_e32 v93, v93
	v_exp_f32_e32 v94, v94
	v_exp_f32_e32 v95, v95
	v_pk_add_f32 v[202:203], v[202:203], v[88:89]
	v_pk_add_f32 v[202:203], v[202:203], v[90:91]
	s_setprio 1
	v_cvt_pk_bf16_f32 v198, v80, v81
	v_cvt_pk_bf16_f32 v199, v82, v83
	v_cvt_pk_bf16_f32 v200, v84, v85
	v_cvt_pk_bf16_f32 v201, v86, v87
	v_pk_add_f32 v[202:203], v[202:203], v[92:93]
	v_cvt_pk_bf16_f32 v80, v88, v89
	v_cvt_pk_bf16_f32 v81, v90, v91
	v_cvt_pk_bf16_f32 v82, v92, v93
	v_cvt_pk_bf16_f32 v83, v94, v95
	v_pk_add_f32 v[202:203], v[202:203], v[94:95]
	v_mfma_f32_32x32x16_bf16 v[48:63], v[148:151], v[198:201], v[48:63]
	ds_read_b64_tr_b16 v[148:149], v188 offset:45056
	ds_read_b64_tr_b16 v[150:151], v188 offset:47616
	v_fma_f32 v64, v64, s88, -v158
	v_fma_f32 v65, v65, s88, -v158
	v_exp_f32_e32 v64, v64
	v_exp_f32_e32 v65, v65
	v_mfma_f32_32x32x16_bf16 v[32:47], v[144:147], v[198:201], v[32:47]
	ds_read_b64_tr_b16 v[144:145], v188 offset:45120
	ds_read_b64_tr_b16 v[146:147], v188 offset:47680
	v_fma_f32 v66, v66, s88, -v158
	v_fma_f32 v67, v67, s88, -v158
	v_exp_f32_e32 v66, v66
	v_exp_f32_e32 v67, v67
	v_pk_add_f32 v[202:203], v[202:203], v[64:65]
	v_mfma_f32_32x32x16_bf16 v[16:31], v[140:143], v[198:201], v[16:31]
	ds_read_b64_tr_b16 v[140:141], v188 offset:45184
	ds_read_b64_tr_b16 v[142:143], v188 offset:47744
	v_fma_f32 v68, v68, s88, -v158
	v_fma_f32 v69, v69, s88, -v158
	v_exp_f32_e32 v68, v68
	v_exp_f32_e32 v69, v69
	v_pk_add_f32 v[202:203], v[202:203], v[66:67]
	v_mfma_f32_32x32x16_bf16 v[0:15], v[136:139], v[198:201], v[0:15]
	ds_read_b64_tr_b16 v[136:137], v188 offset:45248
	ds_read_b64_tr_b16 v[138:139], v188 offset:47808
	v_fma_f32 v70, v70, s88, -v158
	v_fma_f32 v71, v71, s88, -v158
	v_exp_f32_e32 v70, v70
	v_exp_f32_e32 v71, v71
	v_pk_add_f32 v[202:203], v[202:203], v[68:69]
	v_mfma_f32_32x32x16_bf16 v[48:63], v[128:131], v[80:83], v[48:63]
	ds_read_b64_tr_b16 v[128:129], v188 offset:50176
	ds_read_b64_tr_b16 v[130:131], v188 offset:52736
	v_fma_f32 v72, v72, s88, -v158
	v_fma_f32 v73, v73, s88, -v158
	v_exp_f32_e32 v72, v72
	v_exp_f32_e32 v73, v73
	v_pk_add_f32 v[202:203], v[202:203], v[70:71]
	v_mfma_f32_32x32x16_bf16 v[32:47], v[132:135], v[80:83], v[32:47]
	ds_read_b64_tr_b16 v[132:133], v188 offset:50240
	ds_read_b64_tr_b16 v[134:135], v188 offset:52800
	v_fma_f32 v74, v74, s88, -v158
	v_fma_f32 v75, v75, s88, -v158
	v_exp_f32_e32 v74, v74
	v_exp_f32_e32 v75, v75
	v_pk_add_f32 v[202:203], v[202:203], v[72:73]
	s_waitcnt lgkmcnt(14)
	v_mfma_f32_32x32x16_bf16 v[16:31], v[190:193], v[80:83], v[16:31]
	ds_read_b64_tr_b16 v[190:191], v188 offset:50304
	ds_read_b64_tr_b16 v[192:193], v188 offset:52864
	v_fma_f32 v76, v76, s88, -v158
	v_fma_f32 v77, v77, s88, -v158
	v_exp_f32_e32 v76, v76
	v_exp_f32_e32 v77, v77
	v_pk_add_f32 v[202:203], v[202:203], v[74:75]
	s_waitcnt lgkmcnt(14)
	v_mfma_f32_32x32x16_bf16 v[0:15], v[194:197], v[80:83], v[0:15]
	ds_read_b64_tr_b16 v[194:195], v188 offset:50368
	ds_read_b64_tr_b16 v[196:197], v188 offset:52928
	v_fma_f32 v78, v78, s88, -v158
	v_fma_f32 v79, v79, s88, -v158
	v_exp_f32_e32 v78, v78
	v_exp_f32_e32 v79, v79
	v_pk_add_f32 v[202:203], v[202:203], v[76:77]
	v_cvt_pk_bf16_f32 v84, v64, v65
	v_cvt_pk_bf16_f32 v85, v66, v67
	v_cvt_pk_bf16_f32 v86, v68, v69
	v_cvt_pk_bf16_f32 v87, v70, v71
	v_pk_add_f32 v[202:203], v[202:203], v[78:79]
	v_cvt_pk_bf16_f32 v198, v72, v73
	v_cvt_pk_bf16_f32 v199, v74, v75
	v_cvt_pk_bf16_f32 v200, v76, v77
	v_cvt_pk_bf16_f32 v201, v78, v79
	v_add_f32_e32 v189, v202, v203
	v_add_f32_e32 v153, v153, v189
	s_waitcnt lgkmcnt(14)
	v_mfma_f32_32x32x16_bf16 v[48:63], v[148:151], v[84:87], v[48:63]
	s_waitcnt lgkmcnt(12)
	v_mfma_f32_32x32x16_bf16 v[32:47], v[144:147], v[84:87], v[32:47]
	s_waitcnt lgkmcnt(10)
	v_mfma_f32_32x32x16_bf16 v[16:31], v[140:143], v[84:87], v[16:31]
	s_waitcnt lgkmcnt(8)
	v_mfma_f32_32x32x16_bf16 v[0:15], v[136:139], v[84:87], v[0:15]
	s_waitcnt lgkmcnt(6)
	v_mfma_f32_32x32x16_bf16 v[48:63], v[128:131], v[198:201], v[48:63]
	s_waitcnt lgkmcnt(4)
	v_mfma_f32_32x32x16_bf16 v[32:47], v[132:135], v[198:201], v[32:47]
	s_waitcnt lgkmcnt(2)
	v_mfma_f32_32x32x16_bf16 v[16:31], v[190:193], v[198:201], v[16:31]
	s_waitcnt lgkmcnt(0)
	v_mfma_f32_32x32x16_bf16 v[0:15], v[194:197], v[198:201], v[0:15]
	s_setprio 0
	s_andn2_b64 vcc, exec, s[90:91]
	s_cbranch_vccnz .LBB0_315
